# weight-copy queue: ticket granularity halved (8 items = one per wave per ticket instead of 16) to shorten the phase tail
# speedup vs baseline: 1.0155x; 1.0058x over previous
.LBB0_240:
	s_and_b32 s4, s43, 1
	s_and_saveexec_b64 s[0:1], s[40:41]
	s_lshl_b32 s5, s4, 2
	s_add_i32 s5, s5, 0
	s_add_i32 s5, s5, 0x20830
	v_mov_b32_e32 v0, s5
	ds_write_b32 v0, v66
	s_or_b64 exec, exec, s[0:1]
	s_lshl_b32 s0, s4, 2
	s_add_i32 s0, s0, 0
	s_add_i32 s0, s0, 0x20830
	v_mov_b32_e32 v0, s0
	s_waitcnt lgkmcnt(0)
	s_barrier
	ds_read_b32 v0, v0
	s_mov_b64 s[0:1], -1
	s_waitcnt lgkmcnt(0)
	v_readfirstlane_b32 s4, v0
	s_lshl_b32 s5, s42, 1
	s_cmp_ge_i32 s4, s5
	v_readfirstlane_b32 s5, v0
	s_cbranch_scc1 .LBB0_239
	s_and_saveexec_b64 s[0:1], s[40:41]
	s_cbranch_execz .LBB0_247
	s_mov_b64 s[36:37], exec
	v_mbcnt_lo_u32_b32 v0, s36, 0
	v_mbcnt_hi_u32_b32 v0, s37, v0
	v_cmp_eq_u32_e32 vcc, 0, v0
	s_and_saveexec_b64 s[28:29], vcc
	s_cbranch_execz .LBB0_246
	s_bcnt1_i32_b64 s5, s[36:37]
	v_mov_b32_e32 v1, s5
	global_atomic_add v66, v65, v1, s[16:17] sc0

.LBB0_247:
	s_or_b64 exec, exec, s[0:1]
	s_lshl_b32 s50, s4, 3
	s_cmpk_gt_i32 s4, 0x23f
	v_readlane_b32 s0, v254, 49
	s_cselect_b64 s[62:63], -1, 0
	s_add_i32 s50, s50, s0
	s_mov_b32 s0, 0
	s_mov_b64 s[48:49], 0
	s_branch .LBB0_250
